# attention epilogue: bf16 rounding by v_cvt_pk_bf16_f32 instead of the integer bit-16/add3 sequence (same RNE result), on top of the b128 V-fragment layout version
# baseline (speedup 1.0000x reference)
; __device__ __forceinline__ void dattn_unit(LAS unsigned char* lds, int b, int h, int qb, const bf16* Q, const bf16* K, const bf16* V, bf16* YB, float lam, const float* subg, float oml, int tid) {
;     ...
;     const float l1 = lsum[0] + __shfl_xor(lsum[0], 32), l2 = lsum[1] + __shfl_xor(lsum[1], 32);
;     const float i1 = 1.0f / l1, i2 = lam / l2; float ss = 0.f;
; #pragma unroll
;     for (int cb = 0; cb < 4; ++cb)
; #pragma unroll
;         for (int r = 0; r < 16; ++r) { const float y = o[0][cb][r] * i1 - o[1][cb][r] * i2; o[0][cb][r] = y; ss += y * y; }
.LBB0_219:
	v_cmp_lt_i32_e32 vcc, v252, v246
	s_nop 3
	v_mov_b32_e32 v135, v98
	v_mov_b32_e32 v98, v97
	v_cndmask_b32_e32 v128, v245, v252, vcc
	v_lshlrev_b32_e32 v139, 2, v128
	ds_bpermute_b32 v128, v139, v179
	ds_bpermute_b32 v129, v139, v181
	s_waitcnt lgkmcnt(0)
	s_barrier
	v_add_f32_e32 v128, v179, v128
	v_div_scale_f32 v130, s[46:47], v128, v128, 1.0
	v_rcp_f32_e32 v131, v130
	v_add_f32_e32 v129, v181, v129
	v_lshlrev_b32_e32 v208, 1, v160
	s_add_i32 s55, s55, 1
	v_fma_f32 v132, -v130, v131, 1.0
	v_fmac_f32_e32 v131, v132, v131
	v_div_scale_f32 v132, vcc, 1.0, v128, 1.0
	v_mul_f32_e32 v133, v132, v131
	v_fma_f32 v134, -v130, v133, v132
	v_fmac_f32_e32 v133, v134, v131
	v_fma_f32 v130, -v130, v133, v132
	v_div_fmas_f32 v130, v130, v131, v133
	v_div_fixup_f32 v136, v130, v128, 1.0
	v_div_scale_f32 v128, s[46:47], v129, v129, v186
	v_rcp_f32_e32 v130, v128
	v_mov_b32_e32 v134, v96
	s_cmp_lg_u32 s55, 4
	v_fma_f32 v131, -v128, v130, 1.0
	v_fmac_f32_e32 v130, v131, v130
	v_div_scale_f32 v131, vcc, v186, v129, v186
	v_mul_f32_e32 v132, v131, v130
	v_fma_f32 v133, -v128, v132, v131
	v_fmac_f32_e32 v132, v133, v130
	v_fma_f32 v128, -v128, v132, v131
	v_div_fmas_f32 v128, v128, v130, v132
	v_div_fixup_f32 v138, v128, v129, v186
	v_pk_mul_f32 v[12:13], v[12:13], v[138:139] op_sel_hi:[1,0]
	v_mov_b32_e32 v129, v114
	v_pk_fma_f32 v[28:29], v[28:29], v[136:137], v[12:13] op_sel_hi:[1,0,1] neg_lo:[0,0,1] neg_hi:[0,0,1]
	v_pk_mul_f32 v[12:13], v[14:15], v[138:139] op_sel_hi:[1,0]
	v_mov_b32_e32 v114, v113
	v_pk_fma_f32 v[30:31], v[30:31], v[136:137], v[12:13] op_sel_hi:[1,0,1] neg_lo:[0,0,1] neg_hi:[0,0,1]
	v_lshlrev_b32_e32 v137, 2, v160
	v_pk_mul_f32 v[96:97], v[98:99], v[138:139] op_sel_hi:[1,0]
	v_mov_b32_e32 v98, v100
	v_mov_b32_e32 v99, v102
	v_mov_b32_e32 v128, v112
	v_pk_mul_f32 v[134:135], v[134:135], v[138:139] op_sel_hi:[1,0]
	v_pk_fma_f32 v[112:113], v[114:115], v[136:137], v[96:97] op_sel_hi:[1,0,1] neg_lo:[0,0,1] neg_hi:[0,0,1]
	v_mov_b32_e32 v96, v116
	v_mov_b32_e32 v97, v118
	v_pk_mul_f32 v[98:99], v[98:99], v[138:139] op_sel_hi:[1,0]
	v_mov_b32_e32 v102, v101
	v_pk_fma_f32 v[128:129], v[128:129], v[136:137], v[134:135] op_sel_hi:[1,0,1] neg_lo:[0,0,1] neg_hi:[0,0,1]
	v_pk_fma_f32 v[134:135], v[96:97], v[136:137], v[98:99] op_sel_hi:[1,0,1] neg_lo:[0,0,1] neg_hi:[0,0,1]
	v_mov_b32_e32 v118, v117
	v_pk_mul_f32 v[96:97], v[102:103], v[138:139] op_sel_hi:[1,0]
	v_mov_b32_e32 v98, v104
	v_mov_b32_e32 v99, v106
	v_pk_fma_f32 v[118:119], v[118:119], v[136:137], v[96:97] op_sel_hi:[1,0,1] neg_lo:[0,0,1] neg_hi:[0,0,1]
	v_mov_b32_e32 v96, v120
	v_mov_b32_e32 v97, v122
	v_pk_mul_f32 v[98:99], v[98:99], v[138:139] op_sel_hi:[1,0]
	v_mov_b32_e32 v106, v105
	v_pk_fma_f32 v[116:117], v[96:97], v[136:137], v[98:99] op_sel_hi:[1,0,1] neg_lo:[0,0,1] neg_hi:[0,0,1]
	v_mov_b32_e32 v122, v121
	v_pk_mul_f32 v[96:97], v[106:107], v[138:139] op_sel_hi:[1,0]
	v_mov_b32_e32 v98, v108
	v_mov_b32_e32 v99, v110
	v_pk_fma_f32 v[106:107], v[122:123], v[136:137], v[96:97] op_sel_hi:[1,0,1] neg_lo:[0,0,1] neg_hi:[0,0,1]
	v_mov_b32_e32 v96, v124
	v_mov_b32_e32 v97, v126
	v_pk_mul_f32 v[98:99], v[98:99], v[138:139] op_sel_hi:[1,0]
	v_mov_b32_e32 v110, v109
	v_pk_fma_f32 v[102:103], v[96:97], v[136:137], v[98:99] op_sel_hi:[1,0,1] neg_lo:[0,0,1] neg_hi:[0,0,1]
	v_mov_b32_e32 v126, v125
	v_pk_mul_f32 v[96:97], v[110:111], v[138:139] op_sel_hi:[1,0]
	v_mov_b32_e32 v98, v64
	v_mov_b32_e32 v99, v66
	v_mov_b32_e32 v66, v65
	v_pk_fma_f32 v[104:105], v[126:127], v[136:137], v[96:97] op_sel_hi:[1,0,1] neg_lo:[0,0,1] neg_hi:[0,0,1]
	v_mov_b32_e32 v96, v80
	v_mov_b32_e32 v97, v82
	v_pk_mul_f32 v[98:99], v[98:99], v[138:139] op_sel_hi:[1,0]
	v_mov_b32_e32 v82, v81
	v_pk_mul_f32 v[64:65], v[66:67], v[138:139] op_sel_hi:[1,0]
	v_mov_b32_e32 v66, v68
	v_mov_b32_e32 v67, v70
	v_pk_fma_f32 v[100:101], v[96:97], v[136:137], v[98:99] op_sel_hi:[1,0,1] neg_lo:[0,0,1] neg_hi:[0,0,1]
	v_pk_fma_f32 v[98:99], v[82:83], v[136:137], v[64:65] op_sel_hi:[1,0,1] neg_lo:[0,0,1] neg_hi:[0,0,1]
	v_mov_b32_e32 v64, v84
	v_mov_b32_e32 v65, v86
	v_pk_mul_f32 v[66:67], v[66:67], v[138:139] op_sel_hi:[1,0]
	v_mov_b32_e32 v70, v69
	v_pk_fma_f32 v[96:97], v[64:65], v[136:137], v[66:67] op_sel_hi:[1,0,1] neg_lo:[0,0,1] neg_hi:[0,0,1]
	v_mov_b32_e32 v86, v85
	v_pk_mul_f32 v[64:65], v[70:71], v[138:139] op_sel_hi:[1,0]
	v_mov_b32_e32 v66, v72
	v_mov_b32_e32 v67, v74
	v_pk_fma_f32 v[82:83], v[86:87], v[136:137], v[64:65] op_sel_hi:[1,0,1] neg_lo:[0,0,1] neg_hi:[0,0,1]
	v_mov_b32_e32 v64, v88
	v_mov_b32_e32 v65, v90
	v_pk_mul_f32 v[66:67], v[66:67], v[138:139] op_sel_hi:[1,0]
	v_mov_b32_e32 v74, v73
	v_pk_fma_f32 v[80:81], v[64:65], v[136:137], v[66:67] op_sel_hi:[1,0,1] neg_lo:[0,0,1] neg_hi:[0,0,1]
	v_mov_b32_e32 v90, v89
	v_pk_mul_f32 v[64:65], v[74:75], v[138:139] op_sel_hi:[1,0]
	v_mov_b32_e32 v66, v76
	v_mov_b32_e32 v67, v78
	v_pk_fma_f32 v[74:75], v[90:91], v[136:137], v[64:65] op_sel_hi:[1,0,1] neg_lo:[0,0,1] neg_hi:[0,0,1]
	v_mov_b32_e32 v64, v92
	v_mov_b32_e32 v65, v94
	v_pk_mul_f32 v[66:67], v[66:67], v[138:139] op_sel_hi:[1,0]
	v_mov_b32_e32 v78, v77
	v_pk_fma_f32 v[72:73], v[64:65], v[136:137], v[66:67] op_sel_hi:[1,0,1] neg_lo:[0,0,1] neg_hi:[0,0,1]
	v_mov_b32_e32 v94, v93
	v_pk_mul_f32 v[64:65], v[78:79], v[138:139] op_sel_hi:[1,0]
	v_mov_b32_e32 v66, v32
	v_mov_b32_e32 v67, v34
	v_mov_b32_e32 v34, v33
	v_pk_fma_f32 v[70:71], v[94:95], v[136:137], v[64:65] op_sel_hi:[1,0,1] neg_lo:[0,0,1] neg_hi:[0,0,1]
	v_mov_b32_e32 v64, v48
	v_mov_b32_e32 v65, v50
	v_pk_mul_f32 v[66:67], v[66:67], v[138:139] op_sel_hi:[1,0]
	v_mov_b32_e32 v50, v49
	v_pk_mul_f32 v[32:33], v[34:35], v[138:139] op_sel_hi:[1,0]
; __device__ __forceinline__ void dattn_unit(LAS unsigned char* lds, int b, int h, int qb, const bf16* Q, const bf16* K, const bf16* V, bf16* YB, float lam, const float* subg, float oml, int tid) {
;     ...
;     const float l1 = lsum[0] + __shfl_xor(lsum[0], 32), l2 = lsum[1] + __shfl_xor(lsum[1], 32);
;     const float i1 = 1.0f / l1, i2 = lam / l2; float ss = 0.f;
; #pragma unroll
;     for (int cb = 0; cb < 4; ++cb)
; #pragma unroll
;         for (int r = 0; r < 16; ++r) { const float y = o[0][cb][r] * i1 - o[1][cb][r] * i2; o[0][cb][r] = y; ss += y * y; }
;     ss += __shfl_xor(ss, 32);
;     const float rstd = rsqrtf(ss * (1.f / 128.f) + EPS) * oml;
;     bf16* op = YB + (rowb + q) * 1024 + h * 128;
; #pragma unroll
;     for (int cb = 0; cb < 4; ++cb)
; #pragma unroll
;         for (int rg = 0; rg < 4; ++rg) { const int c = 32 * cb + 8 * rg + 4 * hi; const f32x4 g = *(const f32x4*)(subg + c);
	v_mov_b32_e32 v34, v36
	v_mov_b32_e32 v35, v38
	v_pk_fma_f32 v[68:69], v[64:65], v[136:137], v[66:67] op_sel_hi:[1,0,1] neg_lo:[0,0,1] neg_hi:[0,0,1]
	v_pk_fma_f32 v[66:67], v[50:51], v[136:137], v[32:33] op_sel_hi:[1,0,1] neg_lo:[0,0,1] neg_hi:[0,0,1]
	v_mov_b32_e32 v32, v52
	v_mov_b32_e32 v33, v54
	v_pk_mul_f32 v[34:35], v[34:35], v[138:139] op_sel_hi:[1,0]
	v_mov_b32_e32 v38, v37
	v_pk_fma_f32 v[64:65], v[32:33], v[136:137], v[34:35] op_sel_hi:[1,0,1] neg_lo:[0,0,1] neg_hi:[0,0,1]
	v_mov_b32_e32 v54, v53
	v_pk_mul_f32 v[32:33], v[38:39], v[138:139] op_sel_hi:[1,0]
	v_mov_b32_e32 v34, v40
	v_mov_b32_e32 v35, v42
	v_pk_fma_f32 v[50:51], v[54:55], v[136:137], v[32:33] op_sel_hi:[1,0,1] neg_lo:[0,0,1] neg_hi:[0,0,1]
	v_mov_b32_e32 v32, v56
	v_mov_b32_e32 v33, v58
	v_pk_mul_f32 v[34:35], v[34:35], v[138:139] op_sel_hi:[1,0]
	v_mov_b32_e32 v42, v41
	v_pk_fma_f32 v[48:49], v[32:33], v[136:137], v[34:35] op_sel_hi:[1,0,1] neg_lo:[0,0,1] neg_hi:[0,0,1]
	v_mov_b32_e32 v58, v57
	v_pk_mul_f32 v[32:33], v[42:43], v[138:139] op_sel_hi:[1,0]
	v_mov_b32_e32 v34, v44
	v_mov_b32_e32 v35, v46
	v_pk_fma_f32 v[38:39], v[58:59], v[136:137], v[32:33] op_sel_hi:[1,0,1] neg_lo:[0,0,1] neg_hi:[0,0,1]
	v_mov_b32_e32 v32, v60
	v_mov_b32_e32 v33, v62
	v_pk_mul_f32 v[34:35], v[34:35], v[138:139] op_sel_hi:[1,0]
	v_mov_b32_e32 v46, v45
	v_pk_fma_f32 v[36:37], v[32:33], v[136:137], v[34:35] op_sel_hi:[1,0,1] neg_lo:[0,0,1] neg_hi:[0,0,1]
	v_mov_b32_e32 v62, v61
	v_pk_mul_f32 v[32:33], v[46:47], v[138:139] op_sel_hi:[1,0]
	v_mov_b32_e32 v47, v2
	v_mov_b32_e32 v2, v1
	global_load_dwordx4 v[12:15], v137, s[4:5]
	global_load_dwordx4 v[212:215], v137, s[4:5] offset:32
	global_load_dwordx4 v[216:219], v137, s[4:5] offset:64
	global_load_dwordx4 v[220:223], v137, s[4:5] offset:96
	global_load_dwordx4 v[224:227], v137, s[4:5] offset:128
	global_load_dwordx4 v[228:231], v137, s[4:5] offset:160
	global_load_dwordx4 v[232:235], v137, s[4:5] offset:192
	global_load_dwordx4 v[236:239], v137, s[4:5] offset:224
	global_load_dwordx4 v[240:243], v137, s[4:5] offset:256
	global_load_dwordx4 v[192:195], v137, s[4:5] offset:288
	global_load_dwordx4 v[196:199], v137, s[4:5] offset:320
	global_load_dwordx4 v[200:203], v137, s[4:5] offset:352
	global_load_dwordx4 v[204:207], v137, s[4:5] offset:384
	global_load_dwordx4 v[164:167], v137, s[4:5] offset:416
	global_load_dwordx4 v[168:171], v137, s[4:5] offset:448
	global_load_dwordx4 v[172:175], v137, s[4:5] offset:480
	v_pk_mul_f32 v[140:141], v[128:129], v[128:129]
	v_pk_mul_f32 v[142:143], v[112:113], v[112:113]
	v_pk_fma_f32 v[34:35], v[62:63], v[136:137], v[32:33] op_sel_hi:[1,0,1] neg_lo:[0,0,1] neg_hi:[0,0,1]
	v_mov_b32_e32 v33, v18
	v_mov_b32_e32 v46, v0
	v_mov_b32_e32 v18, v17
	v_pk_mul_f32 v[0:1], v[2:3], v[138:139] op_sel_hi:[1,0]
	v_pk_mul_f32 v[144:145], v[134:135], v[134:135]
	v_pk_fma_f32 v[18:19], v[18:19], v[136:137], v[0:1] op_sel_hi:[1,0,1] neg_lo:[0,0,1] neg_hi:[0,0,1]
	v_mov_b32_e32 v0, v20
	v_add_f32_e32 v20, v140, v142
	v_add_f32_e32 v20, v141, v20
	v_add_f32_e32 v20, v143, v20
	v_pk_mul_f32 v[146:147], v[118:119], v[118:119]
	v_add_f32_e32 v20, v144, v20
	v_add_f32_e32 v20, v146, v20
	v_add_f32_e32 v20, v145, v20
	v_pk_mul_f32 v[148:149], v[116:117], v[116:117]
	v_add_f32_e32 v20, v147, v20
	v_pk_mul_f32 v[120:121], v[106:107], v[106:107]
	v_add_f32_e32 v20, v148, v20
	v_add_f32_e32 v20, v120, v20
	v_add_f32_e32 v20, v149, v20
	v_pk_mul_f32 v[122:123], v[102:103], v[102:103]
	v_add_f32_e32 v20, v121, v20
	v_pk_mul_f32 v[108:109], v[104:105], v[104:105]
	v_add_f32_e32 v20, v122, v20
	v_add_f32_e32 v20, v108, v20
	v_add_f32_e32 v20, v123, v20
	v_pk_mul_f32 v[110:111], v[100:101], v[100:101]
	v_add_f32_e32 v20, v109, v20
	v_pk_mul_f32 v[124:125], v[98:99], v[98:99]
	v_add_f32_e32 v20, v110, v20
	v_add_f32_e32 v20, v124, v20
	v_add_f32_e32 v20, v111, v20
	v_pk_mul_f32 v[126:127], v[96:97], v[96:97]
	v_add_f32_e32 v20, v125, v20
	v_pk_mul_f32 v[84:85], v[82:83], v[82:83]
	v_add_f32_e32 v20, v126, v20
	v_add_f32_e32 v20, v84, v20
	v_add_f32_e32 v20, v127, v20
	v_pk_mul_f32 v[86:87], v[80:81], v[80:81]
	v_add_f32_e32 v20, v85, v20
	v_pk_mul_f32 v[88:89], v[74:75], v[74:75]
	v_add_f32_e32 v20, v86, v20
	v_add_f32_e32 v20, v88, v20
	v_add_f32_e32 v20, v87, v20
	v_pk_mul_f32 v[90:91], v[72:73], v[72:73]
	v_add_f32_e32 v20, v89, v20
	v_pk_mul_f32 v[76:77], v[70:71], v[70:71]
	v_add_f32_e32 v20, v90, v20
	v_add_f32_e32 v20, v76, v20
	v_add_f32_e32 v20, v91, v20
	v_pk_mul_f32 v[78:79], v[68:69], v[68:69]
	v_add_f32_e32 v20, v77, v20
	v_pk_mul_f32 v[92:93], v[66:67], v[66:67]
	v_add_f32_e32 v20, v78, v20
	v_add_f32_e32 v20, v92, v20
	v_add_f32_e32 v20, v79, v20
	v_pk_mul_f32 v[94:95], v[64:65], v[64:65]
	v_add_f32_e32 v20, v93, v20
	v_pk_mul_f32 v[52:53], v[50:51], v[50:51]
	v_add_f32_e32 v20, v94, v20
	v_add_f32_e32 v20, v52, v20
	v_add_f32_e32 v20, v95, v20
	v_pk_mul_f32 v[54:55], v[48:49], v[48:49]
	v_add_f32_e32 v20, v53, v20
	v_pk_mul_f32 v[40:41], v[38:39], v[38:39]
	v_add_f32_e32 v20, v54, v20
	v_add_f32_e32 v20, v40, v20
	v_add_f32_e32 v20, v55, v20
	v_pk_mul_f32 v[42:43], v[36:37], v[36:37]
	v_add_f32_e32 v20, v41, v20
	v_pk_mul_f32 v[44:45], v[34:35], v[34:35]
	v_add_f32_e32 v20, v42, v20
	v_mov_b32_e32 v32, v16
	v_pk_mul_f32 v[46:47], v[46:47], v[138:139] op_sel_hi:[1,0]
	v_add_f32_e32 v20, v44, v20
	v_pk_fma_f32 v[32:33], v[32:33], v[136:137], v[46:47] op_sel_hi:[1,0,1] neg_lo:[0,0,1] neg_hi:[0,0,1]
	v_mov_b32_e32 v2, v4
	v_mov_b32_e32 v3, v6
	v_add_f32_e32 v20, v43, v20
	v_pk_mul_f32 v[46:47], v[32:33], v[32:33]
	v_mov_b32_e32 v1, v22
	v_pk_mul_f32 v[2:3], v[2:3], v[138:139] op_sel_hi:[1,0]
	v_mov_b32_e32 v6, v5
; __device__ __forceinline__ unsigned pk2(float lo, float hi) { return f2bf(lo) | (f2bf(hi) << 16); }
; __device__ __forceinline__ void dattn_unit(LAS unsigned char* lds, int b, int h, int qb, const bf16* Q, const bf16* K, const bf16* V, bf16* YB, float lam, const float* subg, float oml, int tid) {
;     ...
;     ss += __shfl_xor(ss, 32);
;     const float rstd = rsqrtf(ss * (1.f / 128.f) + EPS) * oml;
;     bf16* op = YB + (rowb + q) * 1024 + h * 128;
; #pragma unroll
;     for (int cb = 0; cb < 4; ++cb)
; #pragma unroll
;         for (int rg = 0; rg < 4; ++rg) { const int c = 32 * cb + 8 * rg + 4 * hi; const f32x4 g = *(const f32x4*)(subg + c);
;             v2u wv; wv.x = pk2(o[0][cb][4 * rg + 0] * rstd * g.x, o[0][cb][4 * rg + 1] * rstd * g.y); wv.y = pk2(o[0][cb][4 * rg + 2] * rstd * g.z, o[0][cb][4 * rg + 3] * rstd * g.w);
;             *(v2u*)(op + c) = wv; }
	v_add_f32_e32 v20, v45, v20
	v_pk_mul_f32 v[56:57], v[18:19], v[18:19]
	v_pk_fma_f32 v[16:17], v[0:1], v[136:137], v[2:3] op_sel_hi:[1,0,1] neg_lo:[0,0,1] neg_hi:[0,0,1]
	v_mov_b32_e32 v22, v21
	v_pk_mul_f32 v[0:1], v[6:7], v[138:139] op_sel_hi:[1,0]
	v_add_f32_e32 v20, v46, v20
	v_pk_fma_f32 v[4:5], v[22:23], v[136:137], v[0:1] op_sel_hi:[1,0,1] neg_lo:[0,0,1] neg_hi:[0,0,1]
	v_add_f32_e32 v20, v56, v20
	v_mov_b32_e32 v0, v5
	v_mov_b32_e32 v1, v17
	v_mov_b32_e32 v2, v8
	v_mov_b32_e32 v3, v10
	v_add_f32_e32 v20, v47, v20
	v_pk_mul_f32 v[6:7], v[0:1], v[0:1]
	v_mov_b32_e32 v0, v24
	v_mov_b32_e32 v1, v26
	v_pk_mul_f32 v[2:3], v[2:3], v[138:139] op_sel_hi:[1,0]
	v_mov_b32_e32 v10, v9
	v_add_f32_e32 v20, v57, v20
	v_pk_fma_f32 v[2:3], v[0:1], v[136:137], v[2:3] op_sel_hi:[1,0,1] neg_lo:[0,0,1] neg_hi:[0,0,1]
	v_mov_b32_e32 v26, v25
	v_pk_mul_f32 v[0:1], v[10:11], v[138:139] op_sel_hi:[1,0]
	v_fmac_f32_e32 v20, v16, v16
	v_pk_fma_f32 v[0:1], v[26:27], v[136:137], v[0:1] op_sel_hi:[1,0,1] neg_lo:[0,0,1] neg_hi:[0,0,1]
	v_fmac_f32_e32 v20, v4, v4
	v_mov_b32_e32 v8, v0
	v_mov_b32_e32 v9, v2
	v_add_f32_e32 v7, v7, v20
	v_pk_mul_f32 v[8:9], v[8:9], v[8:9]
	v_add_f32_e32 v6, v6, v7
	v_mov_b32_e32 v10, v1
	v_mov_b32_e32 v11, v3
	v_add_f32_e32 v6, v9, v6
	v_pk_mul_f32 v[10:11], v[10:11], v[10:11]
	v_add_f32_e32 v6, v8, v6
	v_add_f32_e32 v6, v11, v6
	v_pk_mul_f32 v[130:131], v[28:29], v[28:29]
	v_add_f32_e32 v6, v10, v6
	v_add_f32_e32 v6, v130, v6
	v_pk_mul_f32 v[132:133], v[30:31], v[30:31]
	v_add_f32_e32 v6, v131, v6
	v_add_f32_e32 v6, v132, v6
	v_add_f32_e32 v6, v133, v6
	ds_bpermute_b32 v7, v139, v6
	s_waitcnt vmcnt(15)
	v_mov_b32_e32 v114, v12
	v_mov_b32_e32 v115, v14
	v_mov_b32_e32 v14, v13
	v_lshl_add_u64 v[12:13], v[176:177], 0, v[208:209]
	s_waitcnt lgkmcnt(0)
	v_add_f32_e32 v6, v6, v7
	v_fmamk_f32 v6, v6, 0x3c000000, v210
	v_cmp_gt_f32_e32 vcc, s39, v6
	v_mul_f32_e32 v7, 0x4b800000, v6
	s_nop 0
	v_cndmask_b32_e32 v6, v6, v7, vcc
	v_rsq_f32_e32 v6, v6
	s_nop 0
	v_mul_f32_e32 v7, 0x45800000, v6
	v_cndmask_b32_e32 v6, v6, v7, vcc
	v_mul_f32_e32 v6, v187, v6
	v_pk_mul_f32 v[8:9], v[128:129], v[6:7] op_sel_hi:[1,0]
	v_pk_mul_f32 v[10:11], v[112:113], v[6:7] op_sel_hi:[1,0]
	v_pk_mul_f32 v[8:9], v[114:115], v[8:9]
	v_pk_mul_f32 v[10:11], v[14:15], v[10:11]
	v_cvt_pk_bf16_f32 v9, v9, v11
	v_cvt_pk_bf16_f32 v8, v8, v10
	global_store_dwordx2 v[12:13], v[8:9], off
	v_pk_mul_f32 v[14:15], v[134:135], v[6:7] op_sel_hi:[1,0]
	s_waitcnt vmcnt(15)
	v_mov_b32_e32 v8, v212
	v_mov_b32_e32 v9, v213
	v_mov_b32_e32 v10, v214
	v_mov_b32_e32 v11, v215
	v_mov_b32_e32 v20, v8
	v_mov_b32_e32 v21, v10
	v_pk_mul_f32 v[14:15], v[20:21], v[14:15]
	v_pk_mul_f32 v[20:21], v[118:119], v[6:7] op_sel_hi:[1,0]
	v_mov_b32_e32 v10, v9
	v_pk_mul_f32 v[8:9], v[10:11], v[20:21]
	v_cvt_pk_bf16_f32 v9, v15, v9
	v_cvt_pk_bf16_f32 v8, v14, v8
	global_store_dwordx2 v[12:13], v[8:9], off offset:16
	v_pk_mul_f32 v[14:15], v[116:117], v[6:7] op_sel_hi:[1,0]
	s_waitcnt vmcnt(15)
	v_mov_b32_e32 v8, v216
	v_mov_b32_e32 v9, v217
	v_mov_b32_e32 v10, v218
	v_mov_b32_e32 v11, v219
	v_mov_b32_e32 v20, v8
	v_mov_b32_e32 v21, v10
	v_pk_mul_f32 v[14:15], v[20:21], v[14:15]
	v_pk_mul_f32 v[20:21], v[106:107], v[6:7] op_sel_hi:[1,0]
	v_mov_b32_e32 v10, v9
	v_pk_mul_f32 v[8:9], v[10:11], v[20:21]
	v_cvt_pk_bf16_f32 v9, v15, v9
	v_cvt_pk_bf16_f32 v8, v14, v8
	global_store_dwordx2 v[12:13], v[8:9], off offset:32
	v_pk_mul_f32 v[14:15], v[102:103], v[6:7] op_sel_hi:[1,0]
	s_waitcnt vmcnt(15)
	v_mov_b32_e32 v8, v220
	v_mov_b32_e32 v9, v221
	v_mov_b32_e32 v10, v222
	v_mov_b32_e32 v11, v223
	v_mov_b32_e32 v20, v8
	v_mov_b32_e32 v21, v10
	v_pk_mul_f32 v[14:15], v[20:21], v[14:15]
	v_pk_mul_f32 v[20:21], v[104:105], v[6:7] op_sel_hi:[1,0]
	v_mov_b32_e32 v10, v9
	v_pk_mul_f32 v[8:9], v[10:11], v[20:21]
	v_cvt_pk_bf16_f32 v9, v15, v9
	v_cvt_pk_bf16_f32 v8, v14, v8
	global_store_dwordx2 v[12:13], v[8:9], off offset:48
	v_pk_mul_f32 v[14:15], v[100:101], v[6:7] op_sel_hi:[1,0]
	s_waitcnt vmcnt(15)
	v_mov_b32_e32 v8, v224
	v_mov_b32_e32 v9, v225
	v_mov_b32_e32 v10, v226
	v_mov_b32_e32 v11, v227
	v_mov_b32_e32 v20, v8
	v_mov_b32_e32 v21, v10
	v_pk_mul_f32 v[14:15], v[20:21], v[14:15]
	v_pk_mul_f32 v[20:21], v[98:99], v[6:7] op_sel_hi:[1,0]
	v_mov_b32_e32 v10, v9
	v_pk_mul_f32 v[8:9], v[10:11], v[20:21]
	v_cvt_pk_bf16_f32 v9, v15, v9
	v_cvt_pk_bf16_f32 v8, v14, v8
	global_store_dwordx2 v[12:13], v[8:9], off offset:64
	v_pk_mul_f32 v[14:15], v[96:97], v[6:7] op_sel_hi:[1,0]
	s_waitcnt vmcnt(15)
	v_mov_b32_e32 v8, v228
	v_mov_b32_e32 v9, v229
	v_mov_b32_e32 v10, v230
	v_mov_b32_e32 v11, v231
	v_mov_b32_e32 v20, v8
	v_mov_b32_e32 v21, v10
	v_pk_mul_f32 v[14:15], v[20:21], v[14:15]
	v_pk_mul_f32 v[20:21], v[82:83], v[6:7] op_sel_hi:[1,0]
	v_mov_b32_e32 v10, v9
	v_pk_mul_f32 v[8:9], v[10:11], v[20:21]
	v_cvt_pk_bf16_f32 v9, v15, v9
	v_cvt_pk_bf16_f32 v8, v14, v8
	global_store_dwordx2 v[12:13], v[8:9], off offset:80
	v_pk_mul_f32 v[14:15], v[80:81], v[6:7] op_sel_hi:[1,0]
	s_waitcnt vmcnt(15)
; __device__ __forceinline__ unsigned pk2(float lo, float hi) { return f2bf(lo) | (f2bf(hi) << 16); }
; __device__ __forceinline__ void dattn_unit(LAS unsigned char* lds, int b, int h, int qb, const bf16* Q, const bf16* K, const bf16* V, bf16* YB, float lam, const float* subg, float oml, int tid) {
;     ...
; #pragma unroll
;     for (int cb = 0; cb < 4; ++cb)
; #pragma unroll
;         for (int rg = 0; rg < 4; ++rg) { const int c = 32 * cb + 8 * rg + 4 * hi; const f32x4 g = *(const f32x4*)(subg + c);
;             v2u wv; wv.x = pk2(o[0][cb][4 * rg + 0] * rstd * g.x, o[0][cb][4 * rg + 1] * rstd * g.y); wv.y = pk2(o[0][cb][4 * rg + 2] * rstd * g.z, o[0][cb][4 * rg + 3] * rstd * g.w);
;             *(v2u*)(op + c) = wv; }
	v_mov_b32_e32 v8, v232
	v_mov_b32_e32 v9, v233
	v_mov_b32_e32 v10, v234
	v_mov_b32_e32 v11, v235
	v_mov_b32_e32 v20, v8
	v_mov_b32_e32 v21, v10
	v_pk_mul_f32 v[14:15], v[20:21], v[14:15]
	v_pk_mul_f32 v[20:21], v[74:75], v[6:7] op_sel_hi:[1,0]
	v_mov_b32_e32 v10, v9
	v_pk_mul_f32 v[8:9], v[10:11], v[20:21]
	v_cvt_pk_bf16_f32 v9, v15, v9
	v_cvt_pk_bf16_f32 v8, v14, v8
	global_store_dwordx2 v[12:13], v[8:9], off offset:96
	v_pk_mul_f32 v[14:15], v[72:73], v[6:7] op_sel_hi:[1,0]
	s_waitcnt vmcnt(15)
	v_mov_b32_e32 v8, v236
	v_mov_b32_e32 v9, v237
	v_mov_b32_e32 v10, v238
	v_mov_b32_e32 v11, v239
	v_mov_b32_e32 v20, v8
	v_mov_b32_e32 v21, v10
	v_pk_mul_f32 v[14:15], v[20:21], v[14:15]
	v_pk_mul_f32 v[20:21], v[70:71], v[6:7] op_sel_hi:[1,0]
	v_mov_b32_e32 v10, v9
	v_pk_mul_f32 v[8:9], v[10:11], v[20:21]
	v_cvt_pk_bf16_f32 v9, v15, v9
	v_cvt_pk_bf16_f32 v8, v14, v8
	global_store_dwordx2 v[12:13], v[8:9], off offset:112
	v_pk_mul_f32 v[14:15], v[68:69], v[6:7] op_sel_hi:[1,0]
	s_waitcnt vmcnt(15)
	v_mov_b32_e32 v8, v240
	v_mov_b32_e32 v9, v241
	v_mov_b32_e32 v10, v242
	v_mov_b32_e32 v11, v243
	v_mov_b32_e32 v20, v8
	v_mov_b32_e32 v21, v10
	v_pk_mul_f32 v[14:15], v[20:21], v[14:15]
	v_pk_mul_f32 v[20:21], v[66:67], v[6:7] op_sel_hi:[1,0]
	v_mov_b32_e32 v10, v9
	v_pk_mul_f32 v[8:9], v[10:11], v[20:21]
	v_cvt_pk_bf16_f32 v9, v15, v9
	v_cvt_pk_bf16_f32 v8, v14, v8
	global_store_dwordx2 v[12:13], v[8:9], off offset:128
	v_pk_mul_f32 v[14:15], v[64:65], v[6:7] op_sel_hi:[1,0]
	s_waitcnt vmcnt(15)
	v_mov_b32_e32 v8, v192
	v_mov_b32_e32 v9, v193
	v_mov_b32_e32 v10, v194
	v_mov_b32_e32 v11, v195
	v_mov_b32_e32 v20, v8
	v_mov_b32_e32 v21, v10
	v_pk_mul_f32 v[14:15], v[20:21], v[14:15]
	v_pk_mul_f32 v[20:21], v[50:51], v[6:7] op_sel_hi:[1,0]
	v_mov_b32_e32 v10, v9
	v_pk_mul_f32 v[8:9], v[10:11], v[20:21]
	v_cvt_pk_bf16_f32 v9, v15, v9
	v_cvt_pk_bf16_f32 v8, v14, v8
	global_store_dwordx2 v[12:13], v[8:9], off offset:144
	v_pk_mul_f32 v[14:15], v[48:49], v[6:7] op_sel_hi:[1,0]
	s_waitcnt vmcnt(15)
	v_mov_b32_e32 v8, v196
	v_mov_b32_e32 v9, v197
	v_mov_b32_e32 v10, v198
	v_mov_b32_e32 v11, v199
	v_mov_b32_e32 v20, v8
	v_mov_b32_e32 v21, v10
	v_pk_mul_f32 v[14:15], v[20:21], v[14:15]
	v_pk_mul_f32 v[20:21], v[38:39], v[6:7] op_sel_hi:[1,0]
	v_mov_b32_e32 v10, v9
	v_pk_mul_f32 v[8:9], v[10:11], v[20:21]
	v_cvt_pk_bf16_f32 v9, v15, v9
	v_cvt_pk_bf16_f32 v8, v14, v8
	global_store_dwordx2 v[12:13], v[8:9], off offset:160
	v_pk_mul_f32 v[14:15], v[36:37], v[6:7] op_sel_hi:[1,0]
	s_waitcnt vmcnt(15)
	v_mov_b32_e32 v8, v200
	v_mov_b32_e32 v9, v201
	v_mov_b32_e32 v10, v202
	v_mov_b32_e32 v11, v203
	v_mov_b32_e32 v20, v8
	v_mov_b32_e32 v21, v10
	v_pk_mul_f32 v[14:15], v[20:21], v[14:15]
	v_pk_mul_f32 v[20:21], v[34:35], v[6:7] op_sel_hi:[1,0]
	v_mov_b32_e32 v10, v9
	v_pk_mul_f32 v[8:9], v[10:11], v[20:21]
	v_cvt_pk_bf16_f32 v9, v15, v9
	v_cvt_pk_bf16_f32 v8, v14, v8
	global_store_dwordx2 v[12:13], v[8:9], off offset:176
	v_pk_mul_f32 v[14:15], v[32:33], v[6:7] op_sel_hi:[1,0]
	v_pk_mul_f32 v[18:19], v[18:19], v[6:7] op_sel_hi:[1,0]
	s_waitcnt vmcnt(15)
	v_mov_b32_e32 v8, v204
	v_mov_b32_e32 v9, v205
	v_mov_b32_e32 v10, v206
	v_mov_b32_e32 v11, v207
	v_mov_b32_e32 v20, v8
	v_mov_b32_e32 v21, v10
	v_pk_mul_f32 v[14:15], v[20:21], v[14:15]
	v_mov_b32_e32 v10, v9
	v_pk_mul_f32 v[8:9], v[10:11], v[18:19]
	v_cvt_pk_bf16_f32 v9, v15, v9
	v_cvt_pk_bf16_f32 v8, v14, v8
	global_store_dwordx2 v[12:13], v[8:9], off offset:192
	v_pk_mul_f32 v[14:15], v[16:17], v[6:7] op_sel_hi:[1,0]
	v_pk_mul_f32 v[4:5], v[4:5], v[6:7] op_sel_hi:[1,0]
	s_waitcnt vmcnt(15)
	v_mov_b32_e32 v8, v164
	v_mov_b32_e32 v9, v165
	v_mov_b32_e32 v10, v166
	v_mov_b32_e32 v11, v167
	v_mov_b32_e32 v17, v10
	v_mov_b32_e32 v10, v9
	v_mov_b32_e32 v16, v8
	v_pk_mul_f32 v[4:5], v[10:11], v[4:5]
	v_pk_mul_f32 v[14:15], v[16:17], v[14:15]
	v_cvt_pk_bf16_f32 v5, v15, v5
	v_cvt_pk_bf16_f32 v4, v14, v4
	global_store_dwordx2 v[12:13], v[4:5], off offset:208
	v_pk_mul_f32 v[2:3], v[2:3], v[6:7] op_sel_hi:[1,0]
	v_pk_mul_f32 v[0:1], v[0:1], v[6:7] op_sel_hi:[1,0]
	s_waitcnt vmcnt(15)
	v_mov_b32_e32 v8, v168
	v_mov_b32_e32 v9, v169
	v_mov_b32_e32 v10, v170
	v_mov_b32_e32 v11, v171
	v_mov_b32_e32 v4, v8
	v_mov_b32_e32 v5, v10
	v_pk_mul_f32 v[2:3], v[4:5], v[2:3]
	v_mov_b32_e32 v10, v9
	v_pk_mul_f32 v[0:1], v[10:11], v[0:1]
	v_cvt_pk_bf16_f32 v1, v3, v1
	v_cvt_pk_bf16_f32 v0, v2, v0
	global_store_dwordx2 v[12:13], v[0:1], off offset:224
	v_mov_b32_e32 v4, v28
	v_mov_b32_e32 v5, v30
	v_pk_mul_f32 v[4:5], v[4:5], v[6:7] op_sel_hi:[1,0]
	v_mov_b32_e32 v30, v29
	v_pk_mul_f32 v[6:7], v[30:31], v[6:7] op_sel_hi:[1,0]
	s_waitcnt vmcnt(15)
	v_mov_b32_e32 v0, v172
	v_mov_b32_e32 v1, v173
	v_mov_b32_e32 v2, v174
	v_mov_b32_e32 v3, v175
	v_mov_b32_e32 v8, v0
	v_mov_b32_e32 v9, v2
	v_pk_mul_f32 v[4:5], v[8:9], v[4:5]
	v_mov_b32_e32 v2, v1
	v_pk_mul_f32 v[0:1], v[2:3], v[6:7]
	v_cvt_pk_bf16_f32 v1, v5, v1
	v_cvt_pk_bf16_f32 v0, v4, v0
	global_store_dwordx2 v[12:13], v[0:1], off offset:240
	s_cbranch_scc0 .LBB0_213
